# mixer B work items of 128 rows with all loads in flight
# speedup vs baseline: 1.0095x; 1.0003x over previous
.LBB0_696:
	s_or_b64 exec, exec, s[2:3]
	v_readlane_b32 s4, v255, 33
	v_readlane_b32 s5, v255, 34
	s_xor_b64 s[2:3], s[4:5], -1
	v_writelane_b32 v255, s2, 35
	s_lshl_b32 s58, s30, 4
	s_mov_b32 s10, s30
	v_writelane_b32 v255, s3, 36
	s_lshl_b64 s[2:3], s[58:59], 2
	s_add_u32 s2, s44, s2
	s_addc_u32 s3, s45, s3
	v_writelane_b32 v255, s2, 37
	s_mul_i32 s58, s30, 0x300
	s_mov_b32 s11, s59
	v_writelane_b32 v255, s3, 38
	s_and_b64 s[2:3], s[4:5], exec
	s_cselect_b32 s94, 64, 0
	s_cselect_b32 s53, 16, 0
	s_movk_i32 s3, 0x120
	s_cselect_b32 s2, 32, 0
	s_cselect_b32 s3, s3, 0x100
	s_or_b32 s4, s94, s53
	s_or_b32 s4, s4, s2
	s_bitset1_b32 s2, 8
	v_writelane_b32 v255, s2, 39
	s_lshl_b32 s2, s30, 2
	s_add_i32 s6, s4, s3
	v_writelane_b32 v255, s2, 40
	s_addk_i32 s6, 0x350
	s_lshl_b64 s[2:3], s[58:59], 2
	v_readlane_b32 s4, v255, 0
	s_add_u32 s4, s4, s2
	v_readlane_b32 s2, v255, 1
	s_addc_u32 s5, s2, s3
	v_writelane_b32 v255, s4, 41
	s_lshl_b64 s[2:3], s[10:11], 2
	v_mov_b32_e32 v228, 0x8f
	v_writelane_b32 v255, s5, 42
	v_readlane_b32 s4, v254, 16
	v_readlane_b32 s5, v254, 17
	s_add_u32 s4, s4, s2
	s_addc_u32 s5, s5, s3
	v_writelane_b32 v255, s4, 43
	s_barrier
	s_nop 0
	v_writelane_b32 v255, s5, 44
	s_nop 0
	v_readlane_b32 s4, v255, 23
	s_add_u32 s4, s4, s2
	v_readlane_b32 s2, v255, 24
	s_addc_u32 s5, s2, s3
	v_writelane_b32 v255, s4, 45
	s_nop 1
	v_writelane_b32 v255, s5, 46
	v_writelane_b32 v255, s10, 47
	s_lshl_b32 s58, s10, 6
	s_lshl_b64 s[2:3], s[58:59], 2
	v_writelane_b32 v255, s11, 48
	s_nop 0
	v_readlane_b32 s4, v255, 2
	s_add_u32 s34, s4, s2
	v_readlane_b32 s2, v255, 3
	s_addc_u32 s35, s2, s3
	s_branch .LBB0_700

.LBB0_704:
	s_or_b64 exec, exec, s[2:3]
	s_waitcnt lgkmcnt(0)
	s_barrier
	ds_read_b32 v1, v214
	s_mov_b64 s[2:3], -1
	s_waitcnt lgkmcnt(0)
	v_readfirstlane_b32 s7, v1
	s_cmp_ge_i32 s7, s6
	s_cbranch_scc1 .LBB0_699
	v_ashrrev_i32_e32 v218, 8, v212
	v_bfe_u32 v220, v212, 6, 2
	v_and_b32_e32 v219, 15, v212
	v_lshrrev_b32_e32 v223, 4, v212
	v_bfe_u32 v221, v212, 4, 2
	s_cmpk_gt_i32 s7, 0x4f
	s_cbranch_scc0 .LBB0_912
	s_cmpk_gt_u32 s7, 0x24f
	s_cbranch_scc0 .LBB0_876
	s_add_i32 s9, s7, 0xfffffdb0
	s_cmp_ge_i32 s9, s94
	s_cbranch_scc0 .LBB0_836
	s_sub_i32 s10, s9, s94
	s_cmp_ge_i32 s10, s53
	s_cbranch_scc0 .LBB0_723
	s_sub_i32 s11, s10, s53
	v_readlane_b32 s2, v255, 39
	s_cmp_ge_i32 s11, s2
	s_mov_b64 s[2:3], -1
	s_cbranch_scc0 .LBB0_717
	v_readlane_b32 s2, v255, 39
	s_sub_i32 s4, s11, s2
	s_lshl_b32 s4, s4, 7
	s_movk_i32 s5, 0xff
	s_cmp_lt_i32 s4, s68
	s_cselect_b32 s5, 0x7ff, s5
	v_lshrrev_b32_e32 v1, 5, v212
	v_and_b32_e32 v2, 31, v212
	v_lshlrev_b32_e32 v9, 5, v2
	v_lshlrev_b32_e32 v2, 4, v2
	v_lshl_add_u32 v3, v1, 3, s4
	v_and_b32_e32 v4, s5, v3
	v_cmp_ne_u32_e64 s[14:15], 0, v4
	v_add_u32_e32 v6, 7, v4
	v_cmp_ne_u32_e64 s[4:5], s5, v6
	v_mul_u32_u24_e32 v8, 0x600, v3
	v_add_u32_e32 v8, v8, v2
	v_lshlrev_b32_e32 v10, 11, v3
	v_add_u32_e32 v10, v10, v2
	v_readlane_b32 s2, v255, 10
	v_readlane_b32 s3, v255, 11
	v_readlane_b32 s12, v255, 41
	v_readlane_b32 s13, v255, 42
	s_nop 4
	global_load_dwordx4 v[20:23], v8, s[2:3] offset:-1536
	global_load_dwordx4 v[24:27], v8, s[2:3] offset:-512
	global_load_dwordx4 v[28:31], v8, s[2:3]
	global_load_dwordx4 v[32:35], v8, s[2:3] offset:1024
	global_load_dwordx4 v[100:103], v8, s[2:3] offset:512
	v_add_u32_e32 v8, 0x600, v8
	global_load_dwordx4 v[36:39], v8, s[2:3]
	global_load_dwordx4 v[40:43], v8, s[2:3] offset:1024
	global_load_dwordx4 v[104:107], v8, s[2:3] offset:512
	v_add_u32_e32 v8, 0x600, v8
	global_load_dwordx4 v[44:47], v8, s[2:3]
	global_load_dwordx4 v[48:51], v8, s[2:3] offset:1024
	global_load_dwordx4 v[108:111], v8, s[2:3] offset:512
	v_add_u32_e32 v8, 0x600, v8
	global_load_dwordx4 v[52:55], v8, s[2:3]
	global_load_dwordx4 v[56:59], v8, s[2:3] offset:1024
	global_load_dwordx4 v[112:115], v8, s[2:3] offset:512
	v_add_u32_e32 v8, 0x600, v8
	global_load_dwordx4 v[60:63], v8, s[2:3]
	global_load_dwordx4 v[64:67], v8, s[2:3] offset:1024
	global_load_dwordx4 v[116:119], v8, s[2:3] offset:512
	v_add_u32_e32 v8, 0x600, v8
	global_load_dwordx4 v[68:71], v8, s[2:3]
	global_load_dwordx4 v[72:75], v8, s[2:3] offset:1024
	global_load_dwordx4 v[120:123], v8, s[2:3] offset:512
	v_add_u32_e32 v8, 0x600, v8
	global_load_dwordx4 v[76:79], v8, s[2:3]
	global_load_dwordx4 v[80:83], v8, s[2:3] offset:1024
	global_load_dwordx4 v[124:127], v8, s[2:3] offset:512
	v_add_u32_e32 v8, 0x600, v8
	global_load_dwordx4 v[84:87], v8, s[2:3]
	global_load_dwordx4 v[88:91], v8, s[2:3] offset:1024
	global_load_dwordx4 v[128:131], v8, s[2:3] offset:512
	v_add_u32_e32 v8, 0x600, v8
	global_load_dwordx4 v[92:95], v8, s[2:3]
	global_load_dwordx4 v[96:99], v8, s[2:3] offset:1024
	global_load_dwordx4 v[132:135], v9, s[12:13] offset:0
	global_load_dwordx4 v[136:139], v9, s[12:13] offset:16
	global_load_dwordx4 v[140:143], v9, s[12:13] offset:1024
	global_load_dwordx4 v[144:147], v9, s[12:13] offset:1040
	global_load_dwordx4 v[148:151], v9, s[12:13] offset:2048
	global_load_dwordx4 v[152:155], v9, s[12:13] offset:2064
	s_waitcnt vmcnt(0)
	v_cvt_f32_f16_e32 v160, v20
	v_cvt_f32_f16_sdwa v161, v20 dst_sel:DWORD dst_unused:UNUSED_PAD src0_sel:WORD_1
	v_cvt_f32_f16_e32 v162, v21
	v_cvt_f32_f16_sdwa v163, v21 dst_sel:DWORD dst_unused:UNUSED_PAD src0_sel:WORD_1
	v_cvt_f32_f16_e32 v164, v22
	v_cvt_f32_f16_sdwa v165, v22 dst_sel:DWORD dst_unused:UNUSED_PAD src0_sel:WORD_1
	v_cvt_f32_f16_e32 v166, v23
	v_cvt_f32_f16_sdwa v167, v23 dst_sel:DWORD dst_unused:UNUSED_PAD src0_sel:WORD_1
	v_cvt_f32_f16_e32 v168, v24
	v_cvt_f32_f16_sdwa v169, v24 dst_sel:DWORD dst_unused:UNUSED_PAD src0_sel:WORD_1
	v_cvt_f32_f16_e32 v170, v25
	v_cvt_f32_f16_sdwa v171, v25 dst_sel:DWORD dst_unused:UNUSED_PAD src0_sel:WORD_1
	v_cvt_f32_f16_e32 v172, v26
	v_cvt_f32_f16_sdwa v173, v26 dst_sel:DWORD dst_unused:UNUSED_PAD src0_sel:WORD_1
	v_cvt_f32_f16_e32 v174, v27
	v_cvt_f32_f16_sdwa v175, v27 dst_sel:DWORD dst_unused:UNUSED_PAD src0_sel:WORD_1
	v_pk_mul_f32 v[20:21], v[160:161], v[168:169]
	v_pk_mul_f32 v[22:23], v[162:163], v[170:171]
	v_pk_mul_f32 v[24:25], v[164:165], v[172:173]
	v_pk_mul_f32 v[26:27], v[166:167], v[174:175]
	v_cndmask_b32_e64 v20, 0, v20, s[14:15]
	v_cndmask_b32_e64 v21, 0, v21, s[14:15]
	v_cndmask_b32_e64 v22, 0, v22, s[14:15]
	v_cndmask_b32_e64 v23, 0, v23, s[14:15]
	v_cndmask_b32_e64 v24, 0, v24, s[14:15]
	v_cndmask_b32_e64 v25, 0, v25, s[14:15]
	v_cndmask_b32_e64 v26, 0, v26, s[14:15]
	v_cndmask_b32_e64 v27, 0, v27, s[14:15]
	v_cvt_f32_f16_e32 v160, v28
	v_cvt_f32_f16_sdwa v161, v28 dst_sel:DWORD dst_unused:UNUSED_PAD src0_sel:WORD_1
	v_cvt_f32_f16_e32 v162, v29
	v_cvt_f32_f16_sdwa v163, v29 dst_sel:DWORD dst_unused:UNUSED_PAD src0_sel:WORD_1
	v_cvt_f32_f16_e32 v164, v30
	v_cvt_f32_f16_sdwa v165, v30 dst_sel:DWORD dst_unused:UNUSED_PAD src0_sel:WORD_1
	v_cvt_f32_f16_e32 v166, v31
	v_cvt_f32_f16_sdwa v167, v31 dst_sel:DWORD dst_unused:UNUSED_PAD src0_sel:WORD_1
	v_cvt_f32_f16_e32 v168, v32
	v_cvt_f32_f16_sdwa v169, v32 dst_sel:DWORD dst_unused:UNUSED_PAD src0_sel:WORD_1
	v_cvt_f32_f16_e32 v170, v33
	v_cvt_f32_f16_sdwa v171, v33 dst_sel:DWORD dst_unused:UNUSED_PAD src0_sel:WORD_1
	v_cvt_f32_f16_e32 v172, v34
	v_cvt_f32_f16_sdwa v173, v34 dst_sel:DWORD dst_unused:UNUSED_PAD src0_sel:WORD_1
	v_cvt_f32_f16_e32 v174, v35
	v_cvt_f32_f16_sdwa v175, v35 dst_sel:DWORD dst_unused:UNUSED_PAD src0_sel:WORD_1
	v_pk_mul_f32 v[28:29], v[160:161], v[168:169]
	v_pk_mul_f32 v[30:31], v[162:163], v[170:171]
	v_pk_mul_f32 v[32:33], v[164:165], v[172:173]
	v_pk_mul_f32 v[34:35], v[166:167], v[174:175]
	v_cvt_f32_f16_e32 v160, v36
	v_cvt_f32_f16_sdwa v161, v36 dst_sel:DWORD dst_unused:UNUSED_PAD src0_sel:WORD_1
	v_cvt_f32_f16_e32 v162, v37
	v_cvt_f32_f16_sdwa v163, v37 dst_sel:DWORD dst_unused:UNUSED_PAD src0_sel:WORD_1
	v_cvt_f32_f16_e32 v164, v38
	v_cvt_f32_f16_sdwa v165, v38 dst_sel:DWORD dst_unused:UNUSED_PAD src0_sel:WORD_1
	v_cvt_f32_f16_e32 v166, v39
	v_cvt_f32_f16_sdwa v167, v39 dst_sel:DWORD dst_unused:UNUSED_PAD src0_sel:WORD_1
	v_cvt_f32_f16_e32 v168, v40
	v_cvt_f32_f16_sdwa v169, v40 dst_sel:DWORD dst_unused:UNUSED_PAD src0_sel:WORD_1
	v_cvt_f32_f16_e32 v170, v41
	v_cvt_f32_f16_sdwa v171, v41 dst_sel:DWORD dst_unused:UNUSED_PAD src0_sel:WORD_1
	v_cvt_f32_f16_e32 v172, v42
	v_cvt_f32_f16_sdwa v173, v42 dst_sel:DWORD dst_unused:UNUSED_PAD src0_sel:WORD_1
	v_cvt_f32_f16_e32 v174, v43
	v_cvt_f32_f16_sdwa v175, v43 dst_sel:DWORD dst_unused:UNUSED_PAD src0_sel:WORD_1
	v_pk_mul_f32 v[36:37], v[160:161], v[168:169]
	v_pk_mul_f32 v[38:39], v[162:163], v[170:171]
	v_pk_mul_f32 v[40:41], v[164:165], v[172:173]
	v_pk_mul_f32 v[42:43], v[166:167], v[174:175]
	v_cvt_f32_f16_e32 v160, v44
	v_cvt_f32_f16_sdwa v161, v44 dst_sel:DWORD dst_unused:UNUSED_PAD src0_sel:WORD_1
	v_cvt_f32_f16_e32 v162, v45
	v_cvt_f32_f16_sdwa v163, v45 dst_sel:DWORD dst_unused:UNUSED_PAD src0_sel:WORD_1
	v_cvt_f32_f16_e32 v164, v46
	v_cvt_f32_f16_sdwa v165, v46 dst_sel:DWORD dst_unused:UNUSED_PAD src0_sel:WORD_1
	v_cvt_f32_f16_e32 v166, v47
	v_cvt_f32_f16_sdwa v167, v47 dst_sel:DWORD dst_unused:UNUSED_PAD src0_sel:WORD_1
	v_cvt_f32_f16_e32 v168, v48
	v_cvt_f32_f16_sdwa v169, v48 dst_sel:DWORD dst_unused:UNUSED_PAD src0_sel:WORD_1
	v_cvt_f32_f16_e32 v170, v49
	v_cvt_f32_f16_sdwa v171, v49 dst_sel:DWORD dst_unused:UNUSED_PAD src0_sel:WORD_1
	v_cvt_f32_f16_e32 v172, v50
	v_cvt_f32_f16_sdwa v173, v50 dst_sel:DWORD dst_unused:UNUSED_PAD src0_sel:WORD_1
	v_cvt_f32_f16_e32 v174, v51
	v_cvt_f32_f16_sdwa v175, v51 dst_sel:DWORD dst_unused:UNUSED_PAD src0_sel:WORD_1
	v_pk_mul_f32 v[44:45], v[160:161], v[168:169]
	v_pk_mul_f32 v[46:47], v[162:163], v[170:171]
	v_pk_mul_f32 v[48:49], v[164:165], v[172:173]
	v_pk_mul_f32 v[50:51], v[166:167], v[174:175]
	v_cvt_f32_f16_e32 v160, v52
	v_cvt_f32_f16_sdwa v161, v52 dst_sel:DWORD dst_unused:UNUSED_PAD src0_sel:WORD_1
	v_cvt_f32_f16_e32 v162, v53
	v_cvt_f32_f16_sdwa v163, v53 dst_sel:DWORD dst_unused:UNUSED_PAD src0_sel:WORD_1
	v_cvt_f32_f16_e32 v164, v54
	v_cvt_f32_f16_sdwa v165, v54 dst_sel:DWORD dst_unused:UNUSED_PAD src0_sel:WORD_1
	v_cvt_f32_f16_e32 v166, v55
	v_cvt_f32_f16_sdwa v167, v55 dst_sel:DWORD dst_unused:UNUSED_PAD src0_sel:WORD_1
	v_cvt_f32_f16_e32 v168, v56
	v_cvt_f32_f16_sdwa v169, v56 dst_sel:DWORD dst_unused:UNUSED_PAD src0_sel:WORD_1
	v_cvt_f32_f16_e32 v170, v57
	v_cvt_f32_f16_sdwa v171, v57 dst_sel:DWORD dst_unused:UNUSED_PAD src0_sel:WORD_1
	v_cvt_f32_f16_e32 v172, v58
	v_cvt_f32_f16_sdwa v173, v58 dst_sel:DWORD dst_unused:UNUSED_PAD src0_sel:WORD_1
	v_cvt_f32_f16_e32 v174, v59
	v_cvt_f32_f16_sdwa v175, v59 dst_sel:DWORD dst_unused:UNUSED_PAD src0_sel:WORD_1
	v_pk_mul_f32 v[52:53], v[160:161], v[168:169]
	v_pk_mul_f32 v[54:55], v[162:163], v[170:171]
	v_pk_mul_f32 v[56:57], v[164:165], v[172:173]
	v_pk_mul_f32 v[58:59], v[166:167], v[174:175]
	v_cvt_f32_f16_e32 v160, v60
	v_cvt_f32_f16_sdwa v161, v60 dst_sel:DWORD dst_unused:UNUSED_PAD src0_sel:WORD_1
	v_cvt_f32_f16_e32 v162, v61
	v_cvt_f32_f16_sdwa v163, v61 dst_sel:DWORD dst_unused:UNUSED_PAD src0_sel:WORD_1
	v_cvt_f32_f16_e32 v164, v62
	v_cvt_f32_f16_sdwa v165, v62 dst_sel:DWORD dst_unused:UNUSED_PAD src0_sel:WORD_1
	v_cvt_f32_f16_e32 v166, v63
	v_cvt_f32_f16_sdwa v167, v63 dst_sel:DWORD dst_unused:UNUSED_PAD src0_sel:WORD_1
	v_cvt_f32_f16_e32 v168, v64
	v_cvt_f32_f16_sdwa v169, v64 dst_sel:DWORD dst_unused:UNUSED_PAD src0_sel:WORD_1
	v_cvt_f32_f16_e32 v170, v65
	v_cvt_f32_f16_sdwa v171, v65 dst_sel:DWORD dst_unused:UNUSED_PAD src0_sel:WORD_1
	v_cvt_f32_f16_e32 v172, v66
	v_cvt_f32_f16_sdwa v173, v66 dst_sel:DWORD dst_unused:UNUSED_PAD src0_sel:WORD_1
	v_cvt_f32_f16_e32 v174, v67
	v_cvt_f32_f16_sdwa v175, v67 dst_sel:DWORD dst_unused:UNUSED_PAD src0_sel:WORD_1
	v_pk_mul_f32 v[60:61], v[160:161], v[168:169]
	v_pk_mul_f32 v[62:63], v[162:163], v[170:171]
	v_pk_mul_f32 v[64:65], v[164:165], v[172:173]
	v_pk_mul_f32 v[66:67], v[166:167], v[174:175]
	v_cvt_f32_f16_e32 v160, v68
	v_cvt_f32_f16_sdwa v161, v68 dst_sel:DWORD dst_unused:UNUSED_PAD src0_sel:WORD_1
	v_cvt_f32_f16_e32 v162, v69
	v_cvt_f32_f16_sdwa v163, v69 dst_sel:DWORD dst_unused:UNUSED_PAD src0_sel:WORD_1
	v_cvt_f32_f16_e32 v164, v70
	v_cvt_f32_f16_sdwa v165, v70 dst_sel:DWORD dst_unused:UNUSED_PAD src0_sel:WORD_1
	v_cvt_f32_f16_e32 v166, v71
	v_cvt_f32_f16_sdwa v167, v71 dst_sel:DWORD dst_unused:UNUSED_PAD src0_sel:WORD_1
	v_cvt_f32_f16_e32 v168, v72
	v_cvt_f32_f16_sdwa v169, v72 dst_sel:DWORD dst_unused:UNUSED_PAD src0_sel:WORD_1
	v_cvt_f32_f16_e32 v170, v73
	v_cvt_f32_f16_sdwa v171, v73 dst_sel:DWORD dst_unused:UNUSED_PAD src0_sel:WORD_1
	v_cvt_f32_f16_e32 v172, v74
	v_cvt_f32_f16_sdwa v173, v74 dst_sel:DWORD dst_unused:UNUSED_PAD src0_sel:WORD_1
	v_cvt_f32_f16_e32 v174, v75
	v_cvt_f32_f16_sdwa v175, v75 dst_sel:DWORD dst_unused:UNUSED_PAD src0_sel:WORD_1
	v_pk_mul_f32 v[68:69], v[160:161], v[168:169]
	v_pk_mul_f32 v[70:71], v[162:163], v[170:171]
	v_pk_mul_f32 v[72:73], v[164:165], v[172:173]
	v_pk_mul_f32 v[74:75], v[166:167], v[174:175]
	v_cvt_f32_f16_e32 v160, v76
	v_cvt_f32_f16_sdwa v161, v76 dst_sel:DWORD dst_unused:UNUSED_PAD src0_sel:WORD_1
	v_cvt_f32_f16_e32 v162, v77
	v_cvt_f32_f16_sdwa v163, v77 dst_sel:DWORD dst_unused:UNUSED_PAD src0_sel:WORD_1
	v_cvt_f32_f16_e32 v164, v78
	v_cvt_f32_f16_sdwa v165, v78 dst_sel:DWORD dst_unused:UNUSED_PAD src0_sel:WORD_1
	v_cvt_f32_f16_e32 v166, v79
	v_cvt_f32_f16_sdwa v167, v79 dst_sel:DWORD dst_unused:UNUSED_PAD src0_sel:WORD_1
	v_cvt_f32_f16_e32 v168, v80
	v_cvt_f32_f16_sdwa v169, v80 dst_sel:DWORD dst_unused:UNUSED_PAD src0_sel:WORD_1
	v_cvt_f32_f16_e32 v170, v81
	v_cvt_f32_f16_sdwa v171, v81 dst_sel:DWORD dst_unused:UNUSED_PAD src0_sel:WORD_1
	v_cvt_f32_f16_e32 v172, v82
	v_cvt_f32_f16_sdwa v173, v82 dst_sel:DWORD dst_unused:UNUSED_PAD src0_sel:WORD_1
	v_cvt_f32_f16_e32 v174, v83
	v_cvt_f32_f16_sdwa v175, v83 dst_sel:DWORD dst_unused:UNUSED_PAD src0_sel:WORD_1
	v_pk_mul_f32 v[76:77], v[160:161], v[168:169]
	v_pk_mul_f32 v[78:79], v[162:163], v[170:171]
	v_pk_mul_f32 v[80:81], v[164:165], v[172:173]
	v_pk_mul_f32 v[82:83], v[166:167], v[174:175]
	v_cvt_f32_f16_e32 v160, v84
	v_cvt_f32_f16_sdwa v161, v84 dst_sel:DWORD dst_unused:UNUSED_PAD src0_sel:WORD_1
	v_cvt_f32_f16_e32 v162, v85
	v_cvt_f32_f16_sdwa v163, v85 dst_sel:DWORD dst_unused:UNUSED_PAD src0_sel:WORD_1
	v_cvt_f32_f16_e32 v164, v86
	v_cvt_f32_f16_sdwa v165, v86 dst_sel:DWORD dst_unused:UNUSED_PAD src0_sel:WORD_1
	v_cvt_f32_f16_e32 v166, v87
	v_cvt_f32_f16_sdwa v167, v87 dst_sel:DWORD dst_unused:UNUSED_PAD src0_sel:WORD_1
	v_cvt_f32_f16_e32 v168, v88
	v_cvt_f32_f16_sdwa v169, v88 dst_sel:DWORD dst_unused:UNUSED_PAD src0_sel:WORD_1
	v_cvt_f32_f16_e32 v170, v89
	v_cvt_f32_f16_sdwa v171, v89 dst_sel:DWORD dst_unused:UNUSED_PAD src0_sel:WORD_1
	v_cvt_f32_f16_e32 v172, v90
	v_cvt_f32_f16_sdwa v173, v90 dst_sel:DWORD dst_unused:UNUSED_PAD src0_sel:WORD_1
	v_cvt_f32_f16_e32 v174, v91
	v_cvt_f32_f16_sdwa v175, v91 dst_sel:DWORD dst_unused:UNUSED_PAD src0_sel:WORD_1
	v_pk_mul_f32 v[84:85], v[160:161], v[168:169]
	v_pk_mul_f32 v[86:87], v[162:163], v[170:171]
	v_pk_mul_f32 v[88:89], v[164:165], v[172:173]
	v_pk_mul_f32 v[90:91], v[166:167], v[174:175]
	v_cvt_f32_f16_e32 v160, v92
	v_cvt_f32_f16_sdwa v161, v92 dst_sel:DWORD dst_unused:UNUSED_PAD src0_sel:WORD_1
	v_cvt_f32_f16_e32 v162, v93
	v_cvt_f32_f16_sdwa v163, v93 dst_sel:DWORD dst_unused:UNUSED_PAD src0_sel:WORD_1
	v_cvt_f32_f16_e32 v164, v94
	v_cvt_f32_f16_sdwa v165, v94 dst_sel:DWORD dst_unused:UNUSED_PAD src0_sel:WORD_1
	v_cvt_f32_f16_e32 v166, v95
	v_cvt_f32_f16_sdwa v167, v95 dst_sel:DWORD dst_unused:UNUSED_PAD src0_sel:WORD_1
	v_cvt_f32_f16_e32 v168, v96
	v_cvt_f32_f16_sdwa v169, v96 dst_sel:DWORD dst_unused:UNUSED_PAD src0_sel:WORD_1
	v_cvt_f32_f16_e32 v170, v97
	v_cvt_f32_f16_sdwa v171, v97 dst_sel:DWORD dst_unused:UNUSED_PAD src0_sel:WORD_1
	v_cvt_f32_f16_e32 v172, v98
	v_cvt_f32_f16_sdwa v173, v98 dst_sel:DWORD dst_unused:UNUSED_PAD src0_sel:WORD_1
	v_cvt_f32_f16_e32 v174, v99
	v_cvt_f32_f16_sdwa v175, v99 dst_sel:DWORD dst_unused:UNUSED_PAD src0_sel:WORD_1
	v_pk_mul_f32 v[92:93], v[160:161], v[168:169]
	v_pk_mul_f32 v[94:95], v[162:163], v[170:171]
	v_pk_mul_f32 v[96:97], v[164:165], v[172:173]
	v_pk_mul_f32 v[98:99], v[166:167], v[174:175]
	v_cndmask_b32_e64 v92, 0, v92, s[4:5]
	v_cndmask_b32_e64 v93, 0, v93, s[4:5]
	v_cndmask_b32_e64 v94, 0, v94, s[4:5]
	v_cndmask_b32_e64 v95, 0, v95, s[4:5]
	v_cndmask_b32_e64 v96, 0, v96, s[4:5]
	v_cndmask_b32_e64 v97, 0, v97, s[4:5]
	v_cndmask_b32_e64 v98, 0, v98, s[4:5]
	v_cndmask_b32_e64 v99, 0, v99, s[4:5]
	v_cvt_f32_f16_e32 v184, v100
	v_cvt_f32_f16_sdwa v185, v100 dst_sel:DWORD dst_unused:UNUSED_PAD src0_sel:WORD_1
	v_cvt_f32_f16_e32 v186, v101
	v_cvt_f32_f16_sdwa v187, v101 dst_sel:DWORD dst_unused:UNUSED_PAD src0_sel:WORD_1
	v_cvt_f32_f16_e32 v188, v102
	v_cvt_f32_f16_sdwa v189, v102 dst_sel:DWORD dst_unused:UNUSED_PAD src0_sel:WORD_1
	v_cvt_f32_f16_e32 v190, v103
	v_cvt_f32_f16_sdwa v191, v103 dst_sel:DWORD dst_unused:UNUSED_PAD src0_sel:WORD_1
	v_pk_mul_f32 v[176:177], v[28:29], v[140:141]
	v_pk_mul_f32 v[178:179], v[30:31], v[142:143]
	v_pk_mul_f32 v[180:181], v[32:33], v[144:145]
	v_pk_mul_f32 v[182:183], v[34:35], v[146:147]
	v_pk_fma_f32 v[176:177], v[20:21], v[132:133], v[176:177]
	v_pk_fma_f32 v[178:179], v[22:23], v[134:135], v[178:179]
	v_pk_fma_f32 v[180:181], v[24:25], v[136:137], v[180:181]
	v_pk_fma_f32 v[182:183], v[26:27], v[138:139], v[182:183]
	v_pk_fma_f32 v[176:177], v[36:37], v[148:149], v[176:177]
	v_pk_fma_f32 v[178:179], v[38:39], v[150:151], v[178:179]
	v_pk_fma_f32 v[180:181], v[40:41], v[152:153], v[180:181]
	v_pk_fma_f32 v[182:183], v[42:43], v[154:155], v[182:183]
	v_pk_mul_f32 v[176:177], v[176:177], v[184:185]
	v_pk_mul_f32 v[178:179], v[178:179], v[186:187]
	v_pk_mul_f32 v[180:181], v[180:181], v[188:189]
	v_pk_mul_f32 v[182:183], v[182:183], v[190:191]
	v_cvt_pk_f16_f32 v192, v176, v177
	v_cvt_pk_f16_f32 v193, v178, v179
	v_cvt_pk_f16_f32 v194, v180, v181
	v_cvt_pk_f16_f32 v195, v182, v183
	global_store_dwordx4 v10, v[192:195], s[64:65] offset:512
	v_add_u32_e32 v10, 0x800, v10
	v_cvt_f32_f16_e32 v184, v104
	v_cvt_f32_f16_sdwa v185, v104 dst_sel:DWORD dst_unused:UNUSED_PAD src0_sel:WORD_1
	v_cvt_f32_f16_e32 v186, v105
	v_cvt_f32_f16_sdwa v187, v105 dst_sel:DWORD dst_unused:UNUSED_PAD src0_sel:WORD_1
	v_cvt_f32_f16_e32 v188, v106
	v_cvt_f32_f16_sdwa v189, v106 dst_sel:DWORD dst_unused:UNUSED_PAD src0_sel:WORD_1
	v_cvt_f32_f16_e32 v190, v107
	v_cvt_f32_f16_sdwa v191, v107 dst_sel:DWORD dst_unused:UNUSED_PAD src0_sel:WORD_1
	v_pk_mul_f32 v[176:177], v[36:37], v[140:141]
	v_pk_mul_f32 v[178:179], v[38:39], v[142:143]
	v_pk_mul_f32 v[180:181], v[40:41], v[144:145]
	v_pk_mul_f32 v[182:183], v[42:43], v[146:147]
	v_pk_fma_f32 v[176:177], v[28:29], v[132:133], v[176:177]
	v_pk_fma_f32 v[178:179], v[30:31], v[134:135], v[178:179]
	v_pk_fma_f32 v[180:181], v[32:33], v[136:137], v[180:181]
	v_pk_fma_f32 v[182:183], v[34:35], v[138:139], v[182:183]
	v_pk_fma_f32 v[176:177], v[44:45], v[148:149], v[176:177]
	v_pk_fma_f32 v[178:179], v[46:47], v[150:151], v[178:179]
	v_pk_fma_f32 v[180:181], v[48:49], v[152:153], v[180:181]
	v_pk_fma_f32 v[182:183], v[50:51], v[154:155], v[182:183]
	v_pk_mul_f32 v[176:177], v[176:177], v[184:185]
	v_pk_mul_f32 v[178:179], v[178:179], v[186:187]
	v_pk_mul_f32 v[180:181], v[180:181], v[188:189]
	v_pk_mul_f32 v[182:183], v[182:183], v[190:191]
	v_cvt_pk_f16_f32 v196, v176, v177
	v_cvt_pk_f16_f32 v197, v178, v179
	v_cvt_pk_f16_f32 v198, v180, v181
	v_cvt_pk_f16_f32 v199, v182, v183
	global_store_dwordx4 v10, v[196:199], s[64:65] offset:512
	v_add_u32_e32 v10, 0x800, v10
	v_cvt_f32_f16_e32 v184, v108
	v_cvt_f32_f16_sdwa v185, v108 dst_sel:DWORD dst_unused:UNUSED_PAD src0_sel:WORD_1
	v_cvt_f32_f16_e32 v186, v109
	v_cvt_f32_f16_sdwa v187, v109 dst_sel:DWORD dst_unused:UNUSED_PAD src0_sel:WORD_1
	v_cvt_f32_f16_e32 v188, v110
	v_cvt_f32_f16_sdwa v189, v110 dst_sel:DWORD dst_unused:UNUSED_PAD src0_sel:WORD_1
	v_cvt_f32_f16_e32 v190, v111
	v_cvt_f32_f16_sdwa v191, v111 dst_sel:DWORD dst_unused:UNUSED_PAD src0_sel:WORD_1
	v_pk_mul_f32 v[176:177], v[44:45], v[140:141]
	v_pk_mul_f32 v[178:179], v[46:47], v[142:143]
	v_pk_mul_f32 v[180:181], v[48:49], v[144:145]
	v_pk_mul_f32 v[182:183], v[50:51], v[146:147]
	v_pk_fma_f32 v[176:177], v[36:37], v[132:133], v[176:177]
	v_pk_fma_f32 v[178:179], v[38:39], v[134:135], v[178:179]
	v_pk_fma_f32 v[180:181], v[40:41], v[136:137], v[180:181]
	v_pk_fma_f32 v[182:183], v[42:43], v[138:139], v[182:183]
	v_pk_fma_f32 v[176:177], v[52:53], v[148:149], v[176:177]
	v_pk_fma_f32 v[178:179], v[54:55], v[150:151], v[178:179]
	v_pk_fma_f32 v[180:181], v[56:57], v[152:153], v[180:181]
	v_pk_fma_f32 v[182:183], v[58:59], v[154:155], v[182:183]
	v_pk_mul_f32 v[176:177], v[176:177], v[184:185]
	v_pk_mul_f32 v[178:179], v[178:179], v[186:187]
	v_pk_mul_f32 v[180:181], v[180:181], v[188:189]
	v_pk_mul_f32 v[182:183], v[182:183], v[190:191]
	v_cvt_pk_f16_f32 v192, v176, v177
	v_cvt_pk_f16_f32 v193, v178, v179
	v_cvt_pk_f16_f32 v194, v180, v181
	v_cvt_pk_f16_f32 v195, v182, v183
	global_store_dwordx4 v10, v[192:195], s[64:65] offset:512
	v_add_u32_e32 v10, 0x800, v10
	v_cvt_f32_f16_e32 v184, v112
	v_cvt_f32_f16_sdwa v185, v112 dst_sel:DWORD dst_unused:UNUSED_PAD src0_sel:WORD_1
	v_cvt_f32_f16_e32 v186, v113
	v_cvt_f32_f16_sdwa v187, v113 dst_sel:DWORD dst_unused:UNUSED_PAD src0_sel:WORD_1
	v_cvt_f32_f16_e32 v188, v114
	v_cvt_f32_f16_sdwa v189, v114 dst_sel:DWORD dst_unused:UNUSED_PAD src0_sel:WORD_1
	v_cvt_f32_f16_e32 v190, v115
	v_cvt_f32_f16_sdwa v191, v115 dst_sel:DWORD dst_unused:UNUSED_PAD src0_sel:WORD_1
	v_pk_mul_f32 v[176:177], v[52:53], v[140:141]
	v_pk_mul_f32 v[178:179], v[54:55], v[142:143]
	v_pk_mul_f32 v[180:181], v[56:57], v[144:145]
	v_pk_mul_f32 v[182:183], v[58:59], v[146:147]
	v_pk_fma_f32 v[176:177], v[44:45], v[132:133], v[176:177]
	v_pk_fma_f32 v[178:179], v[46:47], v[134:135], v[178:179]
	v_pk_fma_f32 v[180:181], v[48:49], v[136:137], v[180:181]
	v_pk_fma_f32 v[182:183], v[50:51], v[138:139], v[182:183]
	v_pk_fma_f32 v[176:177], v[60:61], v[148:149], v[176:177]
	v_pk_fma_f32 v[178:179], v[62:63], v[150:151], v[178:179]
	v_pk_fma_f32 v[180:181], v[64:65], v[152:153], v[180:181]
	v_pk_fma_f32 v[182:183], v[66:67], v[154:155], v[182:183]
	v_pk_mul_f32 v[176:177], v[176:177], v[184:185]
	v_pk_mul_f32 v[178:179], v[178:179], v[186:187]
	v_pk_mul_f32 v[180:181], v[180:181], v[188:189]
	v_pk_mul_f32 v[182:183], v[182:183], v[190:191]
	v_cvt_pk_f16_f32 v196, v176, v177
	v_cvt_pk_f16_f32 v197, v178, v179
	v_cvt_pk_f16_f32 v198, v180, v181
	v_cvt_pk_f16_f32 v199, v182, v183
	global_store_dwordx4 v10, v[196:199], s[64:65] offset:512
	v_add_u32_e32 v10, 0x800, v10
	v_cvt_f32_f16_e32 v184, v116
	v_cvt_f32_f16_sdwa v185, v116 dst_sel:DWORD dst_unused:UNUSED_PAD src0_sel:WORD_1
	v_cvt_f32_f16_e32 v186, v117
	v_cvt_f32_f16_sdwa v187, v117 dst_sel:DWORD dst_unused:UNUSED_PAD src0_sel:WORD_1
	v_cvt_f32_f16_e32 v188, v118
	v_cvt_f32_f16_sdwa v189, v118 dst_sel:DWORD dst_unused:UNUSED_PAD src0_sel:WORD_1
	v_cvt_f32_f16_e32 v190, v119
	v_cvt_f32_f16_sdwa v191, v119 dst_sel:DWORD dst_unused:UNUSED_PAD src0_sel:WORD_1
	v_pk_mul_f32 v[176:177], v[60:61], v[140:141]
	v_pk_mul_f32 v[178:179], v[62:63], v[142:143]
	v_pk_mul_f32 v[180:181], v[64:65], v[144:145]
	v_pk_mul_f32 v[182:183], v[66:67], v[146:147]
	v_pk_fma_f32 v[176:177], v[52:53], v[132:133], v[176:177]
	v_pk_fma_f32 v[178:179], v[54:55], v[134:135], v[178:179]
	v_pk_fma_f32 v[180:181], v[56:57], v[136:137], v[180:181]
	v_pk_fma_f32 v[182:183], v[58:59], v[138:139], v[182:183]
	v_pk_fma_f32 v[176:177], v[68:69], v[148:149], v[176:177]
	v_pk_fma_f32 v[178:179], v[70:71], v[150:151], v[178:179]
	v_pk_fma_f32 v[180:181], v[72:73], v[152:153], v[180:181]
	v_pk_fma_f32 v[182:183], v[74:75], v[154:155], v[182:183]
	v_pk_mul_f32 v[176:177], v[176:177], v[184:185]
	v_pk_mul_f32 v[178:179], v[178:179], v[186:187]
	v_pk_mul_f32 v[180:181], v[180:181], v[188:189]
	v_pk_mul_f32 v[182:183], v[182:183], v[190:191]
	v_cvt_pk_f16_f32 v192, v176, v177
	v_cvt_pk_f16_f32 v193, v178, v179
	v_cvt_pk_f16_f32 v194, v180, v181
	v_cvt_pk_f16_f32 v195, v182, v183
	global_store_dwordx4 v10, v[192:195], s[64:65] offset:512
	v_add_u32_e32 v10, 0x800, v10
	v_cvt_f32_f16_e32 v184, v120
	v_cvt_f32_f16_sdwa v185, v120 dst_sel:DWORD dst_unused:UNUSED_PAD src0_sel:WORD_1
	v_cvt_f32_f16_e32 v186, v121
	v_cvt_f32_f16_sdwa v187, v121 dst_sel:DWORD dst_unused:UNUSED_PAD src0_sel:WORD_1
	v_cvt_f32_f16_e32 v188, v122
	v_cvt_f32_f16_sdwa v189, v122 dst_sel:DWORD dst_unused:UNUSED_PAD src0_sel:WORD_1
	v_cvt_f32_f16_e32 v190, v123
	v_cvt_f32_f16_sdwa v191, v123 dst_sel:DWORD dst_unused:UNUSED_PAD src0_sel:WORD_1
	v_pk_mul_f32 v[176:177], v[68:69], v[140:141]
	v_pk_mul_f32 v[178:179], v[70:71], v[142:143]
	v_pk_mul_f32 v[180:181], v[72:73], v[144:145]
	v_pk_mul_f32 v[182:183], v[74:75], v[146:147]
	v_pk_fma_f32 v[176:177], v[60:61], v[132:133], v[176:177]
	v_pk_fma_f32 v[178:179], v[62:63], v[134:135], v[178:179]
	v_pk_fma_f32 v[180:181], v[64:65], v[136:137], v[180:181]
	v_pk_fma_f32 v[182:183], v[66:67], v[138:139], v[182:183]
	v_pk_fma_f32 v[176:177], v[76:77], v[148:149], v[176:177]
	v_pk_fma_f32 v[178:179], v[78:79], v[150:151], v[178:179]
	v_pk_fma_f32 v[180:181], v[80:81], v[152:153], v[180:181]
	v_pk_fma_f32 v[182:183], v[82:83], v[154:155], v[182:183]
	v_pk_mul_f32 v[176:177], v[176:177], v[184:185]
	v_pk_mul_f32 v[178:179], v[178:179], v[186:187]
	v_pk_mul_f32 v[180:181], v[180:181], v[188:189]
	v_pk_mul_f32 v[182:183], v[182:183], v[190:191]
	v_cvt_pk_f16_f32 v196, v176, v177
	v_cvt_pk_f16_f32 v197, v178, v179
	v_cvt_pk_f16_f32 v198, v180, v181
	v_cvt_pk_f16_f32 v199, v182, v183
	global_store_dwordx4 v10, v[196:199], s[64:65] offset:512
	v_add_u32_e32 v10, 0x800, v10
	v_cvt_f32_f16_e32 v184, v124
	v_cvt_f32_f16_sdwa v185, v124 dst_sel:DWORD dst_unused:UNUSED_PAD src0_sel:WORD_1
	v_cvt_f32_f16_e32 v186, v125
	v_cvt_f32_f16_sdwa v187, v125 dst_sel:DWORD dst_unused:UNUSED_PAD src0_sel:WORD_1
	v_cvt_f32_f16_e32 v188, v126
	v_cvt_f32_f16_sdwa v189, v126 dst_sel:DWORD dst_unused:UNUSED_PAD src0_sel:WORD_1
	v_cvt_f32_f16_e32 v190, v127
	v_cvt_f32_f16_sdwa v191, v127 dst_sel:DWORD dst_unused:UNUSED_PAD src0_sel:WORD_1
	v_pk_mul_f32 v[176:177], v[76:77], v[140:141]
	v_pk_mul_f32 v[178:179], v[78:79], v[142:143]
	v_pk_mul_f32 v[180:181], v[80:81], v[144:145]
	v_pk_mul_f32 v[182:183], v[82:83], v[146:147]
	v_pk_fma_f32 v[176:177], v[68:69], v[132:133], v[176:177]
	v_pk_fma_f32 v[178:179], v[70:71], v[134:135], v[178:179]
	v_pk_fma_f32 v[180:181], v[72:73], v[136:137], v[180:181]
	v_pk_fma_f32 v[182:183], v[74:75], v[138:139], v[182:183]
	v_pk_fma_f32 v[176:177], v[84:85], v[148:149], v[176:177]
	v_pk_fma_f32 v[178:179], v[86:87], v[150:151], v[178:179]
	v_pk_fma_f32 v[180:181], v[88:89], v[152:153], v[180:181]
	v_pk_fma_f32 v[182:183], v[90:91], v[154:155], v[182:183]
	v_pk_mul_f32 v[176:177], v[176:177], v[184:185]
	v_pk_mul_f32 v[178:179], v[178:179], v[186:187]
	v_pk_mul_f32 v[180:181], v[180:181], v[188:189]
	v_pk_mul_f32 v[182:183], v[182:183], v[190:191]
	v_cvt_pk_f16_f32 v192, v176, v177
	v_cvt_pk_f16_f32 v193, v178, v179
	v_cvt_pk_f16_f32 v194, v180, v181
	v_cvt_pk_f16_f32 v195, v182, v183
	global_store_dwordx4 v10, v[192:195], s[64:65] offset:512
	v_add_u32_e32 v10, 0x800, v10
	v_cvt_f32_f16_e32 v184, v128
	v_cvt_f32_f16_sdwa v185, v128 dst_sel:DWORD dst_unused:UNUSED_PAD src0_sel:WORD_1
	v_cvt_f32_f16_e32 v186, v129
	v_cvt_f32_f16_sdwa v187, v129 dst_sel:DWORD dst_unused:UNUSED_PAD src0_sel:WORD_1
	v_cvt_f32_f16_e32 v188, v130
	v_cvt_f32_f16_sdwa v189, v130 dst_sel:DWORD dst_unused:UNUSED_PAD src0_sel:WORD_1
	v_cvt_f32_f16_e32 v190, v131
	v_cvt_f32_f16_sdwa v191, v131 dst_sel:DWORD dst_unused:UNUSED_PAD src0_sel:WORD_1
	v_pk_mul_f32 v[176:177], v[84:85], v[140:141]
	v_pk_mul_f32 v[178:179], v[86:87], v[142:143]
	v_pk_mul_f32 v[180:181], v[88:89], v[144:145]
	v_pk_mul_f32 v[182:183], v[90:91], v[146:147]
	v_pk_fma_f32 v[176:177], v[76:77], v[132:133], v[176:177]
	v_pk_fma_f32 v[178:179], v[78:79], v[134:135], v[178:179]
	v_pk_fma_f32 v[180:181], v[80:81], v[136:137], v[180:181]
	v_pk_fma_f32 v[182:183], v[82:83], v[138:139], v[182:183]
	v_pk_fma_f32 v[176:177], v[92:93], v[148:149], v[176:177]
	v_pk_fma_f32 v[178:179], v[94:95], v[150:151], v[178:179]
	v_pk_fma_f32 v[180:181], v[96:97], v[152:153], v[180:181]
	v_pk_fma_f32 v[182:183], v[98:99], v[154:155], v[182:183]
	v_pk_mul_f32 v[176:177], v[176:177], v[184:185]
	v_pk_mul_f32 v[178:179], v[178:179], v[186:187]
	v_pk_mul_f32 v[180:181], v[180:181], v[188:189]
	v_pk_mul_f32 v[182:183], v[182:183], v[190:191]
	v_cvt_pk_f16_f32 v196, v176, v177
	v_cvt_pk_f16_f32 v197, v178, v179
	v_cvt_pk_f16_f32 v198, v180, v181
	v_cvt_pk_f16_f32 v199, v182, v183
	global_store_dwordx4 v10, v[196:199], s[64:65] offset:512
	s_mov_b64 s[2:3], 0
